# ffn-up: RSX rows prefetched in the K-loop's last trip (counted vmcnt), conv-weight loads first in a hand-written epilogue prologue
# baseline (speedup 1.0000x reference)
; #define PG8_STAGE(bufoff, gbase, voff) do { _Pragma("unroll") for (int _i = 0; _i < 2; ++_i) \
;         __builtin_amdgcn_global_load_lds((const unsigned*)((const char*)(gbase) + (voff)[_i]), (PG8_LAS unsigned*)(lds + (bufoff) + ldsw + _i * 8192), 16, 0, 0); } while (0)
; #define PG8_LDA(dst, b, h) do { _Pragma("unroll") for (int m = 0; m < 4; ++m) _Pragma("unroll") for (int k = 0; k < 2; ++k) dst[m][k] = *(const PG8_LAS bf16x8*)(lds + PG8_SA(b, h) + aoff + m * 2048 + k * 1024); } while (0)
; #define PG8_LDB(dst, b, h) do { _Pragma("unroll") for (int n = 0; n < 2; ++n) _Pragma("unroll") for (int k = 0; k < 2; ++k) dst[n][k] = *(const PG8_LAS bf16x8*)(lds + PG8_SB(b, h) + boff + n * 2048 + k * 1024); } while (0)
; #define PG8_MMA(ai, bj, At, Bt) do { __builtin_amdgcn_s_setprio(1); _Pragma("unroll") for (int m = 0; m < 4; ++m) _Pragma("unroll") for (int n = 0; n < 2; ++n) _Pragma("unroll") for (int k = 0; k < 2; ++k) \
;         acc[ai][bj][m][n] = __builtin_amdgcn_mfma_f32_16x16x32_bf16(Bt[n][k], At[m][k], acc[ai][bj][m][n], 0, 0, 0); __builtin_amdgcn_s_setprio(0); } while (0)
; #define PG8_WAIT_V(n) asm volatile("s_waitcnt vmcnt(" #n ")" ::: "memory")
; #define PG8_WAIT_L(n) asm volatile("s_waitcnt lgkmcnt(" #n ")" ::: "memory")
; #define PG8_BAR __builtin_amdgcn_s_barrier()
; #define PG8_SCHED __builtin_amdgcn_sched_barrier(0)
; template <class Epi, class Sched, bool ALIGN_EPI = false, bool SP2 = false>
; __device__ __forceinline__ void gemm_phase(PG8_LAS unsigned char* lds, const Gemm g, const Sched& S, const Epi& E, const int wave_id  ) {
;     ...
;             PG8_LDB(B0, 0, 0); PG8_LDB(B1, 0, 1); PG8_SCHED; PG8_LDA(At, 0, 0); PG8_STAGE(PG8_SA(1, 1), a1 + hstep, voffA);
;             PG8_WAIT_V(8); PG8_WAIT_L(0); PG8_BAR; PG8_MMA(0, 0, At, B0); PG8_MMA(0, 1, At, B1); PG8_BAR; PG8_SCHED;
;             PG8_LDA(At, 0, 1); PG8_STAGE(PG8_SB(0, 0), b2, voffB); PG8_STAGE(PG8_SB(0, 1), b2 + hstep, voffB); PG8_STAGE(PG8_SA(0, 0), a2, voffA);
;             PG8_WAIT_V(8); PG8_WAIT_L(0); PG8_BAR; PG8_MMA(1, 0, At, B0); PG8_MMA(1, 1, At, B1); PG8_BAR; PG8_SCHED;
; __device__ __forceinline__ float rstd16(const float* rs, int row, float inv_n) { const f32x4* p = (const f32x4*)(rs + 16 * (size_t)row); const f32x4 a = p[0], b = p[1], c = p[2], d = p[3];
;     return rsqrtf(((hsum4(a) + hsum4(b)) + (hsum4(c) + hsum4(d))) * inv_n + EPS); }
.LBB0_2028:
	v_add_u32_e32 v0, s35, v195
	ds_read_b128 v[34:37], v0
	ds_read_b128 v[38:41], v0 offset:1024
	ds_read_b128 v[50:53], v0 offset:2048
	ds_read_b128 v[54:57], v0 offset:3072
	v_add_u32_e32 v0, s92, v195
	ds_read_b128 v[146:149], v0
	ds_read_b128 v[150:153], v0 offset:1024
	ds_read_b128 v[154:157], v0 offset:2048
	ds_read_b128 v[158:161], v0 offset:3072
	s_add_u32 s8, s6, 0xfffc0080
	s_addc_u32 s9, s7, -1
	s_cmp_eq_u32 s73, 12
	s_cselect_b32 s11, s13, s9
	s_cselect_b32 s10, s14, s8
	s_cselect_b32 s9, s15, s41
	s_cselect_b32 s8, s16, s17
	s_cbranch_scc0 .Lefu_rsxskip
	s_and_b64 vcc, exec, s[70:71]
	s_cbranch_vccz .Lefu_rsxskip
	v_readlane_b32 s48, v255, 22
	v_readlane_b32 s49, v255, 23
	v_readlane_b32 vcc_lo, v255, 10
	v_mbcnt_lo_u32_b32 v222, -1, 0
	v_mbcnt_hi_u32_b32 v222, -1, v222
	v_add_u32_e32 v222, vcc_lo, v222
	v_lshl_add_u32 v222, s40, 8, v222
	v_lshlrev_b32_e32 v222, 6, v222
	s_nop 0
	global_load_dwordx4 v[224:227], v222, s[48:49]
	global_load_dwordx4 v[228:231], v222, s[48:49] offset:16
	global_load_dwordx4 v[232:235], v222, s[48:49] offset:32
	global_load_dwordx4 v[248:251], v222, s[48:49] offset:48
.Lefu_rsxskip:
	v_lshl_add_u64 v[210:211], s[6:7], 0, v[170:171]
	s_add_i32 m0, s42, 0xc000
	ds_read_b128 v[174:177], v196
	ds_read_b128 v[178:181], v196 offset:1024
	ds_read_b128 v[182:185], v196 offset:2048
	ds_read_b128 v[186:189], v196 offset:3072
	ds_read_b128 v[190:193], v196 offset:4096
	ds_read_b128 v[198:201], v196 offset:5120
	ds_read_b128 v[202:205], v196 offset:6144
	ds_read_b128 v[206:209], v196 offset:7168
	global_load_lds_dwordx4 v[210:211], off
	v_lshl_add_u64 v[210:211], s[6:7], 0, v[172:173]
	s_add_i32 m0, s42, 0xe000
	s_nop 0
	global_load_lds_dwordx4 v[210:211], off
	s_waitcnt vmcnt(8)
	s_waitcnt lgkmcnt(0)
	s_barrier
	s_setprio 1
	s_waitcnt lgkmcnt(0)
	v_mfma_f32_16x16x32_bf16 v[142:145], v[34:37], v[174:177], v[142:145]
	v_mfma_f32_16x16x32_bf16 v[134:137], v[50:53], v[174:177], v[134:137]
	v_mfma_f32_16x16x32_bf16 v[126:129], v[34:37], v[182:185], v[126:129]
	v_mfma_f32_16x16x32_bf16 v[118:121], v[50:53], v[182:185], v[118:121]
	v_mfma_f32_16x16x32_bf16 v[110:113], v[34:37], v[190:193], v[110:113]
	v_mfma_f32_16x16x32_bf16 v[102:105], v[50:53], v[190:193], v[102:105]
	v_mfma_f32_16x16x32_bf16 v[94:97], v[34:37], v[202:205], v[94:97]
	v_mfma_f32_16x16x32_bf16 v[86:89], v[50:53], v[202:205], v[86:89]
	v_mfma_f32_16x16x32_bf16 v[142:145], v[38:41], v[178:181], v[142:145]
	v_mfma_f32_16x16x32_bf16 v[134:137], v[54:57], v[178:181], v[134:137]
	v_mfma_f32_16x16x32_bf16 v[126:129], v[38:41], v[186:189], v[126:129]
	v_mfma_f32_16x16x32_bf16 v[118:121], v[54:57], v[186:189], v[118:121]
	v_mfma_f32_16x16x32_bf16 v[110:113], v[38:41], v[198:201], v[110:113]
	v_mfma_f32_16x16x32_bf16 v[102:105], v[54:57], v[198:201], v[102:105]
	v_mfma_f32_16x16x32_bf16 v[94:97], v[38:41], v[206:209], v[94:97]
	v_mfma_f32_16x16x32_bf16 v[86:89], v[54:57], v[206:209], v[86:89]
	s_setprio 0
	s_setprio 1
	v_mfma_f32_16x16x32_bf16 v[138:141], v[146:149], v[174:177], v[138:141]
	v_mfma_f32_16x16x32_bf16 v[130:133], v[154:157], v[174:177], v[130:133]
	v_mfma_f32_16x16x32_bf16 v[122:125], v[146:149], v[182:185], v[122:125]
	v_mfma_f32_16x16x32_bf16 v[114:117], v[154:157], v[182:185], v[114:117]
	v_mfma_f32_16x16x32_bf16 v[106:109], v[146:149], v[190:193], v[106:109]
	v_mfma_f32_16x16x32_bf16 v[98:101], v[154:157], v[190:193], v[98:101]
	v_mfma_f32_16x16x32_bf16 v[90:93], v[146:149], v[202:205], v[90:93]
	v_mfma_f32_16x16x32_bf16 v[82:85], v[154:157], v[202:205], v[82:85]
	v_mfma_f32_16x16x32_bf16 v[138:141], v[150:153], v[178:181], v[138:141]
	v_mfma_f32_16x16x32_bf16 v[130:133], v[158:161], v[178:181], v[130:133]
	v_mfma_f32_16x16x32_bf16 v[122:125], v[150:153], v[186:189], v[122:125]
	v_mfma_f32_16x16x32_bf16 v[114:117], v[158:161], v[186:189], v[114:117]
	v_mfma_f32_16x16x32_bf16 v[106:109], v[150:153], v[198:201], v[106:109]
	v_mfma_f32_16x16x32_bf16 v[98:101], v[158:161], v[198:201], v[98:101]
	v_mfma_f32_16x16x32_bf16 v[90:93], v[150:153], v[206:209], v[90:93]
	v_mfma_f32_16x16x32_bf16 v[82:85], v[158:161], v[206:209], v[82:85]
	s_setprio 0
	s_barrier
	s_mov_b32 m0, s43
	v_lshl_add_u64 v[210:211], s[8:9], 0, v[164:165]
	s_add_u32 vcc_lo, s8, 0x40000
	ds_read_b128 v[174:177], v196 offset:16384
	ds_read_b128 v[178:181], v196 offset:17408
	ds_read_b128 v[182:185], v196 offset:18432
	ds_read_b128 v[186:189], v196 offset:19456
	ds_read_b128 v[190:193], v196 offset:20480
	ds_read_b128 v[198:201], v196 offset:21504
	ds_read_b128 v[202:205], v196 offset:22528
	ds_read_b128 v[206:209], v196 offset:23552
	global_load_lds_dwordx4 v[210:211], off
	v_lshl_add_u64 v[212:213], s[8:9], 0, v[168:169]
	s_mov_b32 m0, s85
	s_addc_u32 vcc_hi, s9, 0
	global_load_lds_dwordx4 v[212:213], off
	v_lshl_add_u64 v[214:215], vcc, 0, v[164:165]
	s_mov_b32 m0, s93
	v_lshl_add_u64 v[216:217], s[10:11], 0, v[166:167]
	global_load_lds_dwordx4 v[214:215], off
	v_lshl_add_u64 v[214:215], vcc, 0, v[168:169]
	s_mov_b32 m0, s94
	s_nop 0
	global_load_lds_dwordx4 v[214:215], off
	v_lshl_add_u64 v[214:215], s[10:11], 0, v[162:163]
	s_mov_b32 m0, s42
	s_nop 0
	global_load_lds_dwordx4 v[214:215], off
	s_mov_b32 m0, s64
	s_nop 0
	global_load_lds_dwordx4 v[216:217], off
	s_waitcnt vmcnt(8)
	s_waitcnt lgkmcnt(0)
	s_barrier
; #define PG8_STAGE(bufoff, gbase, voff) do { _Pragma("unroll") for (int _i = 0; _i < 2; ++_i) \
;         __builtin_amdgcn_global_load_lds((const unsigned*)((const char*)(gbase) + (voff)[_i]), (PG8_LAS unsigned*)(lds + (bufoff) + ldsw + _i * 8192), 16, 0, 0); } while (0)
; #define PG8_LDA(dst, b, h) do { _Pragma("unroll") for (int m = 0; m < 4; ++m) _Pragma("unroll") for (int k = 0; k < 2; ++k) dst[m][k] = *(const PG8_LAS bf16x8*)(lds + PG8_SA(b, h) + aoff + m * 2048 + k * 1024); } while (0)
; #define PG8_LDB(dst, b, h) do { _Pragma("unroll") for (int n = 0; n < 2; ++n) _Pragma("unroll") for (int k = 0; k < 2; ++k) dst[n][k] = *(const PG8_LAS bf16x8*)(lds + PG8_SB(b, h) + boff + n * 2048 + k * 1024); } while (0)
; #define PG8_MMA(ai, bj, At, Bt) do { __builtin_amdgcn_s_setprio(1); _Pragma("unroll") for (int m = 0; m < 4; ++m) _Pragma("unroll") for (int n = 0; n < 2; ++n) _Pragma("unroll") for (int k = 0; k < 2; ++k) \
;         acc[ai][bj][m][n] = __builtin_amdgcn_mfma_f32_16x16x32_bf16(Bt[n][k], At[m][k], acc[ai][bj][m][n], 0, 0, 0); __builtin_amdgcn_s_setprio(0); } while (0)
; #define PG8_WAIT_V(n) asm volatile("s_waitcnt vmcnt(" #n ")" ::: "memory")
; #define PG8_WAIT_L(n) asm volatile("s_waitcnt lgkmcnt(" #n ")" ::: "memory")
; #define PG8_BAR __builtin_amdgcn_s_barrier()
; #define PG8_SCHED __builtin_amdgcn_sched_barrier(0)
; template <class Epi, class Sched, bool ALIGN_EPI = false, bool SP2 = false>
; __device__ __forceinline__ void gemm_phase(PG8_LAS unsigned char* lds, const Gemm g, const Sched& S, const Epi& E, const int wave_id  ) {
;     ...
;             PG8_WAIT_V(8); PG8_WAIT_L(0); PG8_BAR; PG8_MMA(0, 0, At, B0); PG8_MMA(0, 1, At, B1); PG8_BAR; PG8_SCHED;
;             PG8_LDA(At, 0, 1); PG8_STAGE(PG8_SB(0, 0), b2, voffB); PG8_STAGE(PG8_SB(0, 1), b2 + hstep, voffB); PG8_STAGE(PG8_SA(0, 0), a2, voffA);
;             PG8_WAIT_V(8); PG8_WAIT_L(0); PG8_BAR; PG8_MMA(1, 0, At, B0); PG8_MMA(1, 1, At, B1); PG8_BAR; PG8_SCHED;
;             PG8_LDB(B0, 1, 0); PG8_LDB(B1, 1, 1); PG8_SCHED; PG8_LDA(At, 1, 0); PG8_STAGE(PG8_SA(0, 1), a2 + hstep, voffA);
;             PG8_WAIT_V(8); PG8_WAIT_L(0); PG8_BAR; PG8_MMA(0, 0, At, B0); PG8_MMA(0, 1, At, B1); PG8_BAR; PG8_SCHED;
	s_setprio 1
	s_waitcnt lgkmcnt(0)
	v_mfma_f32_16x16x32_bf16 v[78:81], v[34:37], v[174:177], v[78:81]
	v_mfma_f32_16x16x32_bf16 v[70:73], v[50:53], v[174:177], v[70:73]
	v_mfma_f32_16x16x32_bf16 v[62:65], v[34:37], v[182:185], v[62:65]
	v_mfma_f32_16x16x32_bf16 v[46:49], v[50:53], v[182:185], v[46:49]
	v_mfma_f32_16x16x32_bf16 v[30:33], v[34:37], v[190:193], v[30:33]
	v_mfma_f32_16x16x32_bf16 v[22:25], v[50:53], v[190:193], v[22:25]
	v_mfma_f32_16x16x32_bf16 v[14:17], v[34:37], v[202:205], v[14:17]
	v_mfma_f32_16x16x32_bf16 v[6:9], v[50:53], v[202:205], v[6:9]
	v_mfma_f32_16x16x32_bf16 v[78:81], v[38:41], v[178:181], v[78:81]
	v_mfma_f32_16x16x32_bf16 v[70:73], v[54:57], v[178:181], v[70:73]
	v_mfma_f32_16x16x32_bf16 v[62:65], v[38:41], v[186:189], v[62:65]
	v_mfma_f32_16x16x32_bf16 v[46:49], v[54:57], v[186:189], v[46:49]
	v_mfma_f32_16x16x32_bf16 v[30:33], v[38:41], v[198:201], v[30:33]
	v_mfma_f32_16x16x32_bf16 v[22:25], v[54:57], v[198:201], v[22:25]
	v_mfma_f32_16x16x32_bf16 v[14:17], v[38:41], v[206:209], v[14:17]
	v_mfma_f32_16x16x32_bf16 v[6:9], v[54:57], v[206:209], v[6:9]
	s_setprio 0
	s_setprio 1
	v_mfma_f32_16x16x32_bf16 v[42:45], v[154:157], v[182:185], v[42:45]
	v_mfma_f32_16x16x32_bf16 v[26:29], v[146:149], v[190:193], v[26:29]
	v_mfma_f32_16x16x32_bf16 v[18:21], v[154:157], v[190:193], v[18:21]
	v_mfma_f32_16x16x32_bf16 v[10:13], v[146:149], v[202:205], v[10:13]
	v_mfma_f32_16x16x32_bf16 v[2:5], v[154:157], v[202:205], v[2:5]
	v_mfma_f32_16x16x32_bf16 v[34:37], v[146:149], v[174:177], v[74:77]
	v_mfma_f32_16x16x32_bf16 v[38:41], v[154:157], v[174:177], v[66:69]
	v_mfma_f32_16x16x32_bf16 v[50:53], v[146:149], v[182:185], v[58:61]
	v_mfma_f32_16x16x32_bf16 v[42:45], v[158:161], v[186:189], v[42:45]
	v_mfma_f32_16x16x32_bf16 v[26:29], v[150:153], v[198:201], v[26:29]
	v_mfma_f32_16x16x32_bf16 v[18:21], v[158:161], v[198:201], v[18:21]
	v_mfma_f32_16x16x32_bf16 v[10:13], v[150:153], v[206:209], v[10:13]
	v_mfma_f32_16x16x32_bf16 v[2:5], v[158:161], v[206:209], v[2:5]
	v_mfma_f32_16x16x32_bf16 v[34:37], v[150:153], v[178:181], v[34:37]
	v_mfma_f32_16x16x32_bf16 v[38:41], v[158:161], v[178:181], v[38:41]
	v_mfma_f32_16x16x32_bf16 v[50:53], v[150:153], v[186:189], v[50:53]
	s_setprio 0
	s_barrier
	v_add_u32_e32 v0, s20, v195
	ds_read_b128 v[54:57], v0
	ds_read_b128 v[58:61], v0 offset:1024
	ds_read_b128 v[66:69], v0 offset:2048
	ds_read_b128 v[74:77], v0 offset:3072
	v_add_u32_e32 v0, s5, v195
	ds_read_b128 v[146:149], v0
	ds_read_b128 v[150:153], v0 offset:1024
	ds_read_b128 v[154:157], v0 offset:2048
	ds_read_b128 v[158:161], v0 offset:3072
	s_add_u32 s10, s10, 0x40000
	s_addc_u32 s11, s11, 0
	s_mov_b32 m0, s65
	v_lshl_add_u64 v[218:219], s[10:11], 0, v[162:163]
	ds_read_b128 v[174:177], v196 offset:32768
	ds_read_b128 v[178:181], v196 offset:33792
	ds_read_b128 v[182:185], v196 offset:34816
	ds_read_b128 v[186:189], v196 offset:35840
	ds_read_b128 v[190:193], v196 offset:36864
	ds_read_b128 v[198:201], v196 offset:37888
	ds_read_b128 v[202:205], v196 offset:38912
	ds_read_b128 v[206:209], v196 offset:39936
	global_load_lds_dwordx4 v[218:219], off
	v_lshl_add_u64 v[218:219], s[10:11], 0, v[166:167]
	s_mov_b32 m0, s60
	s_nop 0
	global_load_lds_dwordx4 v[218:219], off
	s_waitcnt vmcnt(8)
	s_waitcnt lgkmcnt(0)
	s_barrier
	s_setprio 1
	s_waitcnt lgkmcnt(0)
	v_mfma_f32_16x16x32_bf16 v[142:145], v[54:57], v[174:177], v[142:145]
	v_mfma_f32_16x16x32_bf16 v[134:137], v[66:69], v[174:177], v[134:137]
	v_mfma_f32_16x16x32_bf16 v[126:129], v[54:57], v[182:185], v[126:129]
	v_mfma_f32_16x16x32_bf16 v[118:121], v[66:69], v[182:185], v[118:121]
	v_mfma_f32_16x16x32_bf16 v[110:113], v[54:57], v[190:193], v[110:113]
	v_mfma_f32_16x16x32_bf16 v[102:105], v[66:69], v[190:193], v[102:105]
	v_mfma_f32_16x16x32_bf16 v[94:97], v[54:57], v[202:205], v[94:97]
	v_mfma_f32_16x16x32_bf16 v[86:89], v[66:69], v[202:205], v[86:89]
	v_mfma_f32_16x16x32_bf16 v[142:145], v[58:61], v[178:181], v[142:145]
	v_mfma_f32_16x16x32_bf16 v[134:137], v[74:77], v[178:181], v[134:137]
	v_mfma_f32_16x16x32_bf16 v[126:129], v[58:61], v[186:189], v[126:129]
	v_mfma_f32_16x16x32_bf16 v[118:121], v[74:77], v[186:189], v[118:121]
	v_mfma_f32_16x16x32_bf16 v[110:113], v[58:61], v[198:201], v[110:113]
	v_mfma_f32_16x16x32_bf16 v[102:105], v[74:77], v[198:201], v[102:105]
	v_mfma_f32_16x16x32_bf16 v[94:97], v[58:61], v[206:209], v[94:97]
	v_mfma_f32_16x16x32_bf16 v[86:89], v[74:77], v[206:209], v[86:89]
	s_setprio 0
	s_setprio 1
	v_mfma_f32_16x16x32_bf16 v[138:141], v[146:149], v[174:177], v[138:141]
	v_mfma_f32_16x16x32_bf16 v[130:133], v[154:157], v[174:177], v[130:133]
	v_mfma_f32_16x16x32_bf16 v[122:125], v[146:149], v[182:185], v[122:125]
	v_mfma_f32_16x16x32_bf16 v[114:117], v[154:157], v[182:185], v[114:117]
	v_mfma_f32_16x16x32_bf16 v[106:109], v[146:149], v[190:193], v[106:109]
	v_mfma_f32_16x16x32_bf16 v[98:101], v[154:157], v[190:193], v[98:101]
	v_mfma_f32_16x16x32_bf16 v[90:93], v[146:149], v[202:205], v[90:93]
	v_mfma_f32_16x16x32_bf16 v[82:85], v[154:157], v[202:205], v[82:85]
	v_mfma_f32_16x16x32_bf16 v[138:141], v[150:153], v[178:181], v[138:141]
	v_mfma_f32_16x16x32_bf16 v[130:133], v[158:161], v[178:181], v[130:133]
	v_mfma_f32_16x16x32_bf16 v[122:125], v[150:153], v[186:189], v[122:125]
	v_mfma_f32_16x16x32_bf16 v[114:117], v[158:161], v[186:189], v[114:117]
	v_mfma_f32_16x16x32_bf16 v[106:109], v[150:153], v[198:201], v[106:109]
	v_mfma_f32_16x16x32_bf16 v[98:101], v[158:161], v[198:201], v[98:101]
	v_mfma_f32_16x16x32_bf16 v[90:93], v[150:153], v[206:209], v[90:93]
	v_mfma_f32_16x16x32_bf16 v[82:85], v[158:161], v[206:209], v[82:85]
	s_setprio 0
	s_barrier
; #define PG8_LAS __attribute__((address_space(3)))
; #define PG8_WAIT_V(n) asm volatile("s_waitcnt vmcnt(" #n ")" ::: "memory")
; #define PG8_WAIT_L(n) asm volatile("s_waitcnt lgkmcnt(" #n ")" ::: "memory")
; template <class Epi, class Sched, bool ALIGN_EPI = false, bool SP2 = false>
; __device__ __forceinline__ void gemm_phase(PG8_LAS unsigned char* lds, const Gemm g, const Sched& S, const Epi& E, const int wave_id  ) {
;     ...
;             PG8_LDA(At, 1, 1); PG8_STAGE(PG8_SB(1, 0), b3, voffB); PG8_STAGE(PG8_SB(1, 1), b3 + hstep, voffB); PG8_STAGE(PG8_SA(1, 0), a3, voffA);
;             PG8_WAIT_V(8); PG8_WAIT_L(0); PG8_BAR; PG8_MMA(1, 0, At, B0); PG8_MMA(1, 1, At, B1); PG8_BAR; PG8_SCHED;
;     __device__ __forceinline__ void operator()(const f32x4 (&acc)[2][2][4][2], const Unit& u, int wr, int wc, int fr, int fq) const {
;         EPI_LAUNDER const int cb = wc * 32 + 8 * fq, c0 = u.pn * HALF + cb, tid = (wr * 4 + wc) * 64 + fq * 16 + fr;
;         PG8_LAS float* RST = xch + 1024;
;         if (tid < 256) RST[tid] = rstd16(rsx, u.pm * BM + tid, 1.f / 1024.f);
; #pragma unroll
;         for (int ai = 0; ai < 2; ++ai) if (fr >= 14) { PG8_LAS float* p = xch + ((2 * ai + wr) * 2 + (fr - 14)) * 128 + cb; *(PG8_LAS f32x4*)p = acc[ai][1][3][0]; *(PG8_LAS f32x4*)(p + 4) = acc[ai][1][3][1]; }
;         f32x4 w0[2], w1[2], w2[2], bb[2];
; #pragma unroll
;         for (int n = 0; n < 2; ++n) { w0[n] = *(const f32x4*)(cw + c0 + 4 * n); w1[n] = *(const f32x4*)(cw + DFF + c0 + 4 * n); w2[n] = *(const f32x4*)(cw + 2 * DFF + c0 + 4 * n); bb[n] = *(const f32x4*)(cbias + c0 + 4 * n); }
;         asm volatile("s_waitcnt lgkmcnt(0)" ::: "memory"); __builtin_amdgcn_s_barrier(); asm volatile("" ::: "memory");
; #pragma unroll
;         for (int ai = 0; ai < 2; ++ai) { const int bnd = 2 * ai + wr;
;             f32x4 hp0[2], hp1[2], gp[2];
;             { const int pb_ = bnd > 0 ? bnd - 1 : 0; const float r0 = bnd > 0 ? RST[64 * bnd - 2] : 0.f, r1 = bnd > 0 ? RST[64 * bnd - 1] : 0.f;
; #pragma unroll
;               for (int n = 0; n < 2; ++n) { hp0[n] = *(const PG8_LAS f32x4*)(xch + (pb_ * 2 + 0) * 128 + cb + 4 * n) * r0; hp1[n] = *(const PG8_LAS f32x4*)(xch + (pb_ * 2 + 1) * 128 + cb + 4 * n) * r1; gp[n] = hp0[n]; } }
; #pragma unroll
;             for (int m = 0; m < 4; ++m) { const int rit = ai * HALF + wr * 64 + m * 16 + fr, row = u.pm * BM + rit; const float r = RST[rit];
	s_mov_b32 m0, s21
	v_lshl_add_u64 v[210:211], v[210:211], 0, s[66:67]
	s_add_u32 s8, s8, 0x40080
	ds_read_b128 v[174:177], v196 offset:49152
	ds_read_b128 v[178:181], v196 offset:50176
	ds_read_b128 v[182:185], v196 offset:51200
	ds_read_b128 v[186:189], v196 offset:52224
	ds_read_b128 v[190:193], v196 offset:53248
	ds_read_b128 v[198:201], v196 offset:54272
	ds_read_b128 v[202:205], v196 offset:55296
	ds_read_b128 v[206:209], v196 offset:56320
	global_load_lds_dwordx4 v[210:211], off
	v_lshl_add_u64 v[210:211], v[212:213], 0, s[66:67]
	s_mov_b32 m0, s22
	s_addc_u32 s9, s9, 0
	global_load_lds_dwordx4 v[210:211], off
	v_lshl_add_u64 v[210:211], s[8:9], 0, v[164:165]
	s_mov_b32 m0, s56
	s_nop 0
	global_load_lds_dwordx4 v[210:211], off
	v_lshl_add_u64 v[210:211], s[8:9], 0, v[168:169]
	s_mov_b32 m0, s25
	s_nop 0
	global_load_lds_dwordx4 v[210:211], off
	v_lshl_add_u64 v[210:211], v[214:215], 0, s[66:67]
	s_mov_b32 m0, s23
	s_nop 0
	global_load_lds_dwordx4 v[210:211], off
	v_lshl_add_u64 v[210:211], v[216:217], 0, s[66:67]
	s_mov_b32 m0, s4
	s_nop 0
	global_load_lds_dwordx4 v[210:211], off
	s_waitcnt vmcnt(8)
	s_waitcnt lgkmcnt(0)
	s_barrier
	s_setprio 1
	s_waitcnt lgkmcnt(0)
	v_mfma_f32_16x16x32_bf16 v[78:81], v[54:57], v[174:177], v[78:81]
	v_mfma_f32_16x16x32_bf16 v[70:73], v[66:69], v[174:177], v[70:73]
	v_mfma_f32_16x16x32_bf16 v[62:65], v[54:57], v[182:185], v[62:65]
	v_mfma_f32_16x16x32_bf16 v[46:49], v[66:69], v[182:185], v[46:49]
	v_mfma_f32_16x16x32_bf16 v[30:33], v[54:57], v[190:193], v[30:33]
	v_mfma_f32_16x16x32_bf16 v[22:25], v[66:69], v[190:193], v[22:25]
	v_mfma_f32_16x16x32_bf16 v[14:17], v[54:57], v[202:205], v[14:17]
	v_mfma_f32_16x16x32_bf16 v[6:9], v[66:69], v[202:205], v[6:9]
	v_mfma_f32_16x16x32_bf16 v[78:81], v[58:61], v[178:181], v[78:81]
	v_mfma_f32_16x16x32_bf16 v[70:73], v[74:77], v[178:181], v[70:73]
	v_mfma_f32_16x16x32_bf16 v[62:65], v[58:61], v[186:189], v[62:65]
	v_mfma_f32_16x16x32_bf16 v[46:49], v[74:77], v[186:189], v[46:49]
	v_mfma_f32_16x16x32_bf16 v[30:33], v[58:61], v[198:201], v[30:33]
	v_mfma_f32_16x16x32_bf16 v[22:25], v[74:77], v[198:201], v[22:25]
	v_mfma_f32_16x16x32_bf16 v[14:17], v[58:61], v[206:209], v[14:17]
	v_mfma_f32_16x16x32_bf16 v[6:9], v[74:77], v[206:209], v[6:9]
	s_setprio 0
	s_setprio 1
	v_mfma_f32_16x16x32_bf16 v[34:37], v[146:149], v[174:177], v[34:37]
	v_mfma_f32_16x16x32_bf16 v[74:77], v[150:153], v[178:181], v[34:37]
	v_mfma_f32_16x16x32_bf16 v[34:37], v[154:157], v[174:177], v[38:41]
	v_mfma_f32_16x16x32_bf16 v[66:69], v[158:161], v[178:181], v[34:37]
	v_mfma_f32_16x16x32_bf16 v[34:37], v[146:149], v[182:185], v[50:53]
	v_mfma_f32_16x16x32_bf16 v[58:61], v[150:153], v[186:189], v[34:37]
	v_mfma_f32_16x16x32_bf16 v[34:37], v[154:157], v[182:185], v[42:45]
	v_mfma_f32_16x16x32_bf16 v[26:29], v[146:149], v[190:193], v[26:29]
	v_mfma_f32_16x16x32_bf16 v[18:21], v[154:157], v[190:193], v[18:21]
	v_mfma_f32_16x16x32_bf16 v[10:13], v[146:149], v[202:205], v[10:13]
	v_mfma_f32_16x16x32_bf16 v[2:5], v[154:157], v[202:205], v[2:5]
	v_mfma_f32_16x16x32_bf16 v[42:45], v[158:161], v[186:189], v[34:37]
	v_mfma_f32_16x16x32_bf16 v[26:29], v[150:153], v[198:201], v[26:29]
	v_mfma_f32_16x16x32_bf16 v[18:21], v[158:161], v[198:201], v[18:21]
	v_mfma_f32_16x16x32_bf16 v[10:13], v[150:153], v[206:209], v[10:13]
	v_mfma_f32_16x16x32_bf16 v[2:5], v[158:161], v[206:209], v[2:5]
	s_setprio 0
	s_barrier
	s_add_i32 s73, s73, 2
	s_add_u32 s6, s6, 0x100
	s_addc_u32 s7, s7, 0
	s_add_u32 s17, s17, 0x100
	s_addc_u32 s41, s41, 0
	s_cmp_gt_u32 s73, 13
	s_cbranch_scc0 .LBB0_2028
	s_and_b64 vcc, exec, s[70:71]
	s_cbranch_vccz .LBB0_2031
	s_barrier
.LBB0_2031:
	v_mbcnt_lo_u32_b32 v0, -1, 0
	v_mbcnt_hi_u32_b32 v0, -1, v0
	v_readlane_b32 s6, v255, 6
	v_readlane_b32 s16, v255, 2
	v_and_b32_e32 v200, 15, v0
	v_lshrrev_b32_e32 v176, 4, v0
	v_lshl_add_u32 v176, v176, 3, s6
	v_lshlrev_b32_e32 v199, 2, v176
	v_lshl_add_u32 v174, s12, 7, v176
	v_mov_b32_e32 v175, 0
	v_lshlrev_b32_e32 v192, 2, v174
	v_mov_b32_e32 v193, 0
	global_load_dwordx4 v[50:53], v192, s[2:3]
	global_load_dwordx4 v[34:37], v192, s[2:3] offset:16
	global_load_dwordx4 v[158:161], v192, s[62:63]
	global_load_dwordx4 v[146:149], v192, s[62:63] offset:16
	global_load_dwordx4 v[154:157], v192, s[96:97]
	global_load_dwordx4 v[150:153], v192, s[96:97] offset:16
	global_load_dwordx4 v[54:57], v192, s[18:19]
	global_load_dwordx4 v[38:41], v192, s[18:19] offset:16
	v_cmp_lt_u32_e32 vcc, 13, v200
	s_and_saveexec_b64 s[8:9], vcc
	s_lshl_b32 s17, s16, 4
	s_add_i32 s17, s17, s34
	s_add_i32 s17, s17, 0xffffd400
	v_lshl_add_u32 v177, v200, 9, v199
	v_add_u32_e32 v177, s17, v177
	ds_write_b128 v177, v[90:93]
	ds_write_b128 v177, v[82:85] offset:16
	ds_write_b128 v177, v[10:13] offset:2048
	ds_write_b128 v177, v[2:5] offset:2064
	s_or_b64 exec, exec, s[8:9]
	s_and_b64 vcc, exec, s[70:71]
	s_cbranch_vccz .Lefu_norst
	s_waitcnt vmcnt(24)
	v_add_f32_e32 v178, v224, v225
	v_add_f32_e32 v182, v226, v227
	v_add_f32_e32 v179, v228, v229
	v_add_f32_e32 v183, v230, v231
	v_add_f32_e32 v180, v232, v233
	v_add_f32_e32 v184, v234, v235
	v_add_f32_e32 v181, v248, v249
	v_add_f32_e32 v185, v250, v251
	v_add_f32_e32 v178, v178, v182
	v_add_f32_e32 v179, v179, v183
	v_add_f32_e32 v180, v180, v184
	v_add_f32_e32 v181, v181, v185
	v_add_f32_e32 v178, v178, v179
	v_add_f32_e32 v180, v180, v181
	v_add_f32_e32 v178, v178, v180
	v_fmamk_f32 v178, v178, 0x3a800000, v252
	v_mul_f32_e32 v179, 0x4b800000, v178
	v_cmp_gt_f32_e32 vcc, s31, v178
	v_readlane_b32 s17, v255, 10
	s_nop 1
	v_cndmask_b32_e32 v178, v178, v179, vcc
	v_rsq_f32_e32 v178, v178
	v_add_u32_e32 v180, s17, v0
	v_lshl_add_u32 v180, v180, 2, s34
	v_mul_f32_e32 v179, 0x45800000, v178
	v_cndmask_b32_e32 v178, v178, v179, vcc
	ds_write_b32 v180, v178
.Lefu_norst:
	s_waitcnt lgkmcnt(0)
	s_barrier
	v_readlane_b32 s16, v255, 2
	v_cmp_eq_u32_e64 s[6:7], 15, v200
	v_cmp_lt_u32_e64 s[8:9], 13, v200
	v_cmp_eq_u32_e64 s[10:11], 14, v200
	v_cmp_gt_u32_e64 s[48:49], 2, v200
	v_mov_b32_e32 v232, 0xc0135761
	v_mov_b32_e32 v233, 0xc0135761
	v_mov_b32_e32 v234, 0xbdd2d3e8
	v_mov_b32_e32 v235, 0xbdd2d3e8
	v_mov_b32_e32 v218, 1.0
	v_mov_b32_e32 v219, 1.0
	v_or_b32_e32 v197, s16, v200
	v_lshl_add_u32 v197, v197, 2, s34
	s_lshl_b32 s17, s40, 8
	s_add_i32 s17, s17, s16
	v_add_u32_e32 v0, s17, v200
	v_mov_b64_e32 v[238:239], s[36:37]
	s_movk_i32 s41, 0x1600
	v_mad_u64_u32 v[238:239], vcc, v0, s41, v[238:239]
	v_lshl_add_u64 v[238:239], v[174:175], 1, v[238:239]
	s_mov_b32 s14, 0x16000
	s_mov_b32 s15, 0
	s_waitcnt vmcnt(0)
	s_cmp_lg_u32 s16, 0
	s_cbranch_scc1 .Lefu_halo0
	v_mov_b32_e32 v202, 0
	v_mov_b32_e32 v210, 0
	v_mov_b32_e32 v203, 0
	v_mov_b32_e32 v211, 0
	v_mov_b32_e32 v204, 0
	v_mov_b32_e32 v212, 0
	v_mov_b32_e32 v205, 0
	v_mov_b32_e32 v213, 0
	v_mov_b32_e32 v206, 0
	v_mov_b32_e32 v214, 0
	v_mov_b32_e32 v207, 0
	v_mov_b32_e32 v215, 0
	v_mov_b32_e32 v208, 0
	v_mov_b32_e32 v216, 0
	v_mov_b32_e32 v209, 0
	v_mov_b32_e32 v217, 0
	s_branch .Lefu_halo0_done
